# c4 + pipelined EpiRes<false> epilogue for G3 layer 0
# speedup vs baseline: 1.0001x; 1.0001x over previous
;     __device__ __forceinline__ void operator()(const f32x4 (&acc)[2][2][4][2], const Unit& u, int wr, int wc, int fr, int fq) const {
;         const int row0 = u.pm * BM + wr * 64 + fr; const int col0 = u.pn * BM + wc * 32 + 4 * fq;
; #pragma unroll
;         for (int bj = 0; bj < 2; ++bj)
; #pragma unroll
;             for (int n = 0; n < 2; ++n) {
;                 const int col = col0 + bj * HALF + n * 16;
;                 f32x4 gg = {1.f, 1.f, 1.f, 1.f}, bb = {0.f, 0.f, 0.f, 0.f};
;                 if (NORM) { gg = *(const f32x4*)(gam + col); bb = *(const f32x4*)(bet + col); }
; #pragma unroll
;                 for (int ai = 0; ai < 2; ++ai) {
;                     f32x4 xv[4]; f32x2 st[4];
; #pragma unroll
;                     for (int m = 0; m < 4; ++m) { xv[m] = *(const f32x4*)(X + (size_t)(row0 + ai * HALF + m * 16) * D + col);
;                         if (NORM) st[m] = *(const f32x2*)(stats + 2 * (row0 + ai * HALF + m * 16)); }
; #pragma unroll
;                     for (int m = 0; m < 4; ++m) {
;                         f32x4 x = xv[m];
;                         if (NORM) x = (x - st[m].x) * st[m].y * gg + bb;
;                         if (!dry) *(f32x4*)(X + (size_t)(row0 + ai * HALF + m * 16) * D + col) = x * ALPHA + acc[ai][bj][m][n];
;                     }
;                 }
;             }
;     }
.LBB0_282:
	v_lshl_add_u32 v163, s0, 8, v154
	v_lshl_or_b32 v206, s92, 8, v156
	v_lshlrev_b32_e32 v206, 2, v206
	v_lshl_add_u32 v162, v163, 13, v206
	global_load_dwordx4 v[142:145], v162, s[14:15]
	v_add_u32_e32 v206, 0x20000, v162
	global_load_dwordx4 v[146:149], v206, s[14:15]
	v_add_u32_e32 v163, 0x40000, v162
	global_load_dwordx4 v[150:153], v163, s[14:15]
	v_add_u32_e32 v206, 0x60000, v162
	global_load_dwordx4 v[158:161], v206, s[14:15]
	v_add_u32_e32 v163, 0x100000, v162
	global_load_dwordx4 v[174:177], v163, s[14:15]
	v_add_u32_e32 v206, 0x120000, v162
	global_load_dwordx4 v[178:181], v206, s[14:15]
	v_add_u32_e32 v163, 0x140000, v162
	global_load_dwordx4 v[182:185], v163, s[14:15]
	v_add_u32_e32 v206, 0x160000, v162
	global_load_dwordx4 v[186:189], v206, s[14:15]
	global_load_dwordx4 v[190:193], v162, s[14:15] offset:64
	v_add_u32_e32 v206, 0x20000, v162
	global_load_dwordx4 v[194:197], v206, s[14:15] offset:64
	v_add_u32_e32 v163, 0x40000, v162
	global_load_dwordx4 v[198:201], v163, s[14:15] offset:64
	v_add_u32_e32 v206, 0x60000, v162
	global_load_dwordx4 v[202:205], v206, s[14:15] offset:64
	s_waitcnt vmcnt(8)
	v_pk_fma_f32 v[130:131], v[144:145], s[34:35], v[130:131] op_sel_hi:[1,0,1]
	v_pk_fma_f32 v[128:129], v[142:143], s[34:35], v[128:129] op_sel_hi:[1,0,1]
	v_pk_fma_f32 v[126:127], v[148:149], s[34:35], v[126:127] op_sel_hi:[1,0,1]
	v_pk_fma_f32 v[124:125], v[146:147], s[34:35], v[124:125] op_sel_hi:[1,0,1]
	v_pk_fma_f32 v[122:123], v[152:153], s[34:35], v[122:123] op_sel_hi:[1,0,1]
	v_pk_fma_f32 v[120:121], v[150:151], s[34:35], v[120:121] op_sel_hi:[1,0,1]
	v_pk_fma_f32 v[118:119], v[160:161], s[34:35], v[118:119] op_sel_hi:[1,0,1]
	v_pk_fma_f32 v[116:117], v[158:159], s[34:35], v[116:117] op_sel_hi:[1,0,1]
	v_add_u32_e32 v163, 0x100000, v162
	global_load_dwordx4 v[142:145], v163, s[14:15] offset:64
	v_add_u32_e32 v206, 0x120000, v162
	global_load_dwordx4 v[146:149], v206, s[14:15] offset:64
	v_add_u32_e32 v163, 0x140000, v162
	global_load_dwordx4 v[150:153], v163, s[14:15] offset:64
	v_add_u32_e32 v206, 0x160000, v162
	global_load_dwordx4 v[158:161], v206, s[14:15] offset:64
	global_store_dwordx4 v162, v[128:131], s[14:15]
	v_add_u32_e32 v206, 0x20000, v162
	global_store_dwordx4 v206, v[124:127], s[14:15]
	v_add_u32_e32 v163, 0x40000, v162
	global_store_dwordx4 v163, v[120:123], s[14:15]
	v_add_u32_e32 v206, 0x60000, v162
	global_store_dwordx4 v206, v[116:119], s[14:15]
	s_waitcnt vmcnt(12)
	v_pk_fma_f32 v[114:115], v[176:177], s[34:35], v[114:115] op_sel_hi:[1,0,1]
	v_pk_fma_f32 v[112:113], v[174:175], s[34:35], v[112:113] op_sel_hi:[1,0,1]
	v_pk_fma_f32 v[110:111], v[180:181], s[34:35], v[110:111] op_sel_hi:[1,0,1]
	v_pk_fma_f32 v[108:109], v[178:179], s[34:35], v[108:109] op_sel_hi:[1,0,1]
	v_pk_fma_f32 v[106:107], v[184:185], s[34:35], v[106:107] op_sel_hi:[1,0,1]
	v_pk_fma_f32 v[104:105], v[182:183], s[34:35], v[104:105] op_sel_hi:[1,0,1]
	v_pk_fma_f32 v[102:103], v[188:189], s[34:35], v[102:103] op_sel_hi:[1,0,1]
	v_pk_fma_f32 v[100:101], v[186:187], s[34:35], v[100:101] op_sel_hi:[1,0,1]
	global_load_dwordx4 v[174:177], v162, s[14:15] offset:512
	v_add_u32_e32 v206, 0x20000, v162
	global_load_dwordx4 v[178:181], v206, s[14:15] offset:512
	v_add_u32_e32 v163, 0x40000, v162
	global_load_dwordx4 v[182:185], v163, s[14:15] offset:512
	v_add_u32_e32 v206, 0x60000, v162
	global_load_dwordx4 v[186:189], v206, s[14:15] offset:512
	v_add_u32_e32 v163, 0x100000, v162
	global_store_dwordx4 v163, v[112:115], s[14:15]
	v_add_u32_e32 v206, 0x120000, v162
	global_store_dwordx4 v206, v[108:111], s[14:15]
	v_add_u32_e32 v163, 0x140000, v162
	global_store_dwordx4 v163, v[104:107], s[14:15]
	v_add_u32_e32 v206, 0x160000, v162
	global_store_dwordx4 v206, v[100:103], s[14:15]
	s_waitcnt vmcnt(16)
	v_pk_fma_f32 v[98:99], v[192:193], s[34:35], v[98:99] op_sel_hi:[1,0,1]
	v_pk_fma_f32 v[96:97], v[190:191], s[34:35], v[96:97] op_sel_hi:[1,0,1]
	v_pk_fma_f32 v[94:95], v[196:197], s[34:35], v[94:95] op_sel_hi:[1,0,1]
	v_pk_fma_f32 v[92:93], v[194:195], s[34:35], v[92:93] op_sel_hi:[1,0,1]
	v_pk_fma_f32 v[90:91], v[200:201], s[34:35], v[90:91] op_sel_hi:[1,0,1]
	v_pk_fma_f32 v[88:89], v[198:199], s[34:35], v[88:89] op_sel_hi:[1,0,1]
	v_pk_fma_f32 v[86:87], v[204:205], s[34:35], v[86:87] op_sel_hi:[1,0,1]
	v_pk_fma_f32 v[84:85], v[202:203], s[34:35], v[84:85] op_sel_hi:[1,0,1]
	v_add_u32_e32 v163, 0x100000, v162
	global_load_dwordx4 v[190:193], v163, s[14:15] offset:512
	v_add_u32_e32 v206, 0x120000, v162
	global_load_dwordx4 v[194:197], v206, s[14:15] offset:512
	v_add_u32_e32 v163, 0x140000, v162
	global_load_dwordx4 v[198:201], v163, s[14:15] offset:512
	v_add_u32_e32 v206, 0x160000, v162
	global_load_dwordx4 v[202:205], v206, s[14:15] offset:512
	global_store_dwordx4 v162, v[96:99], s[14:15] offset:64
	v_add_u32_e32 v206, 0x20000, v162
	global_store_dwordx4 v206, v[92:95], s[14:15] offset:64
	v_add_u32_e32 v163, 0x40000, v162
	global_store_dwordx4 v163, v[88:91], s[14:15] offset:64
	v_add_u32_e32 v206, 0x60000, v162
	global_store_dwordx4 v206, v[84:87], s[14:15] offset:64
	s_waitcnt vmcnt(20)
;     __device__ __forceinline__ void operator()(const f32x4 (&acc)[2][2][4][2], const Unit& u, int wr, int wc, int fr, int fq) const {
;         const int row0 = u.pm * BM + wr * 64 + fr; const int col0 = u.pn * BM + wc * 32 + 4 * fq;
; #pragma unroll
;         for (int bj = 0; bj < 2; ++bj)
; #pragma unroll
;             for (int n = 0; n < 2; ++n) {
;                 const int col = col0 + bj * HALF + n * 16;
;                 f32x4 gg = {1.f, 1.f, 1.f, 1.f}, bb = {0.f, 0.f, 0.f, 0.f};
;                 if (NORM) { gg = *(const f32x4*)(gam + col); bb = *(const f32x4*)(bet + col); }
; #pragma unroll
;                 for (int ai = 0; ai < 2; ++ai) {
;                     f32x4 xv[4]; f32x2 st[4];
; #pragma unroll
;                     for (int m = 0; m < 4; ++m) { xv[m] = *(const f32x4*)(X + (size_t)(row0 + ai * HALF + m * 16) * D + col);
;                         if (NORM) st[m] = *(const f32x2*)(stats + 2 * (row0 + ai * HALF + m * 16)); }
; #pragma unroll
;                     for (int m = 0; m < 4; ++m) {
;                         f32x4 x = xv[m];
;                         if (NORM) x = (x - st[m].x) * st[m].y * gg + bb;
;                         if (!dry) *(f32x4*)(X + (size_t)(row0 + ai * HALF + m * 16) * D + col) = x * ALPHA + acc[ai][bj][m][n];
;                     }
;                 }
;             }
;     }
	v_pk_fma_f32 v[82:83], v[144:145], s[34:35], v[82:83] op_sel_hi:[1,0,1]
	v_pk_fma_f32 v[80:81], v[142:143], s[34:35], v[80:81] op_sel_hi:[1,0,1]
	v_pk_fma_f32 v[78:79], v[148:149], s[34:35], v[78:79] op_sel_hi:[1,0,1]
	v_pk_fma_f32 v[76:77], v[146:147], s[34:35], v[76:77] op_sel_hi:[1,0,1]
	v_pk_fma_f32 v[74:75], v[152:153], s[34:35], v[74:75] op_sel_hi:[1,0,1]
	v_pk_fma_f32 v[72:73], v[150:151], s[34:35], v[72:73] op_sel_hi:[1,0,1]
	v_pk_fma_f32 v[70:71], v[160:161], s[34:35], v[70:71] op_sel_hi:[1,0,1]
	v_pk_fma_f32 v[68:69], v[158:159], s[34:35], v[68:69] op_sel_hi:[1,0,1]
	global_load_dwordx4 v[142:145], v162, s[14:15] offset:576
	v_add_u32_e32 v206, 0x20000, v162
	global_load_dwordx4 v[146:149], v206, s[14:15] offset:576
	v_add_u32_e32 v163, 0x40000, v162
	global_load_dwordx4 v[150:153], v163, s[14:15] offset:576
	v_add_u32_e32 v206, 0x60000, v162
	global_load_dwordx4 v[158:161], v206, s[14:15] offset:576
	v_add_u32_e32 v163, 0x100000, v162
	global_store_dwordx4 v163, v[80:83], s[14:15] offset:64
	v_add_u32_e32 v206, 0x120000, v162
	global_store_dwordx4 v206, v[76:79], s[14:15] offset:64
	v_add_u32_e32 v163, 0x140000, v162
	global_store_dwordx4 v163, v[72:75], s[14:15] offset:64
	v_add_u32_e32 v206, 0x160000, v162
	global_store_dwordx4 v206, v[68:71], s[14:15] offset:64
	s_waitcnt vmcnt(20)
	v_pk_fma_f32 v[66:67], v[176:177], s[34:35], v[66:67] op_sel_hi:[1,0,1]
	v_pk_fma_f32 v[64:65], v[174:175], s[34:35], v[64:65] op_sel_hi:[1,0,1]
	v_pk_fma_f32 v[62:63], v[180:181], s[34:35], v[62:63] op_sel_hi:[1,0,1]
	v_pk_fma_f32 v[60:61], v[178:179], s[34:35], v[60:61] op_sel_hi:[1,0,1]
	v_pk_fma_f32 v[58:59], v[184:185], s[34:35], v[58:59] op_sel_hi:[1,0,1]
	v_pk_fma_f32 v[56:57], v[182:183], s[34:35], v[56:57] op_sel_hi:[1,0,1]
	v_pk_fma_f32 v[54:55], v[188:189], s[34:35], v[54:55] op_sel_hi:[1,0,1]
	v_pk_fma_f32 v[52:53], v[186:187], s[34:35], v[52:53] op_sel_hi:[1,0,1]
	v_add_u32_e32 v163, 0x100000, v162
	global_load_dwordx4 v[174:177], v163, s[14:15] offset:576
	v_add_u32_e32 v206, 0x120000, v162
	global_load_dwordx4 v[178:181], v206, s[14:15] offset:576
	v_add_u32_e32 v163, 0x140000, v162
	global_load_dwordx4 v[182:185], v163, s[14:15] offset:576
	v_add_u32_e32 v206, 0x160000, v162
	global_load_dwordx4 v[186:189], v206, s[14:15] offset:576
	global_store_dwordx4 v162, v[64:67], s[14:15] offset:512
	v_add_u32_e32 v206, 0x20000, v162
	global_store_dwordx4 v206, v[60:63], s[14:15] offset:512
	v_add_u32_e32 v163, 0x40000, v162
	global_store_dwordx4 v163, v[56:59], s[14:15] offset:512
	v_add_u32_e32 v206, 0x60000, v162
	global_store_dwordx4 v206, v[52:55], s[14:15] offset:512
	s_waitcnt vmcnt(20)
	v_pk_fma_f32 v[50:51], v[192:193], s[34:35], v[50:51] op_sel_hi:[1,0,1]
	v_pk_fma_f32 v[48:49], v[190:191], s[34:35], v[48:49] op_sel_hi:[1,0,1]
	v_pk_fma_f32 v[46:47], v[196:197], s[34:35], v[46:47] op_sel_hi:[1,0,1]
	v_pk_fma_f32 v[44:45], v[194:195], s[34:35], v[44:45] op_sel_hi:[1,0,1]
	v_pk_fma_f32 v[42:43], v[200:201], s[34:35], v[42:43] op_sel_hi:[1,0,1]
	v_pk_fma_f32 v[40:41], v[198:199], s[34:35], v[40:41] op_sel_hi:[1,0,1]
	v_pk_fma_f32 v[38:39], v[204:205], s[34:35], v[38:39] op_sel_hi:[1,0,1]
	v_pk_fma_f32 v[36:37], v[202:203], s[34:35], v[36:37] op_sel_hi:[1,0,1]
	v_add_u32_e32 v163, 0x100000, v162
	global_store_dwordx4 v163, v[48:51], s[14:15] offset:512
	v_add_u32_e32 v206, 0x120000, v162
	global_store_dwordx4 v206, v[44:47], s[14:15] offset:512
	v_add_u32_e32 v163, 0x140000, v162
	global_store_dwordx4 v163, v[40:43], s[14:15] offset:512
	v_add_u32_e32 v206, 0x160000, v162
	global_store_dwordx4 v206, v[36:39], s[14:15] offset:512
	s_waitcnt vmcnt(16)
	v_pk_fma_f32 v[34:35], v[144:145], s[34:35], v[34:35] op_sel_hi:[1,0,1]
	v_pk_fma_f32 v[32:33], v[142:143], s[34:35], v[32:33] op_sel_hi:[1,0,1]
	v_pk_fma_f32 v[30:31], v[148:149], s[34:35], v[30:31] op_sel_hi:[1,0,1]
	v_pk_fma_f32 v[28:29], v[146:147], s[34:35], v[28:29] op_sel_hi:[1,0,1]
	v_pk_fma_f32 v[26:27], v[152:153], s[34:35], v[26:27] op_sel_hi:[1,0,1]
	v_pk_fma_f32 v[24:25], v[150:151], s[34:35], v[24:25] op_sel_hi:[1,0,1]
	v_pk_fma_f32 v[22:23], v[160:161], s[34:35], v[22:23] op_sel_hi:[1,0,1]
	v_pk_fma_f32 v[20:21], v[158:159], s[34:35], v[20:21] op_sel_hi:[1,0,1]
	global_store_dwordx4 v162, v[32:35], s[14:15] offset:576
	v_add_u32_e32 v206, 0x20000, v162
	global_store_dwordx4 v206, v[28:31], s[14:15] offset:576
	v_add_u32_e32 v163, 0x40000, v162
	global_store_dwordx4 v163, v[24:27], s[14:15] offset:576
	v_add_u32_e32 v206, 0x60000, v162
	global_store_dwordx4 v206, v[20:23], s[14:15] offset:576
	s_waitcnt vmcnt(12)
	v_pk_fma_f32 v[18:19], v[176:177], s[34:35], v[18:19] op_sel_hi:[1,0,1]
	v_pk_fma_f32 v[16:17], v[174:175], s[34:35], v[16:17] op_sel_hi:[1,0,1]
	v_pk_fma_f32 v[14:15], v[180:181], s[34:35], v[14:15] op_sel_hi:[1,0,1]
	v_pk_fma_f32 v[12:13], v[178:179], s[34:35], v[12:13] op_sel_hi:[1,0,1]
	v_pk_fma_f32 v[10:11], v[184:185], s[34:35], v[10:11] op_sel_hi:[1,0,1]
	v_pk_fma_f32 v[8:9], v[182:183], s[34:35], v[8:9] op_sel_hi:[1,0,1]
	v_pk_fma_f32 v[6:7], v[188:189], s[34:35], v[6:7] op_sel_hi:[1,0,1]
	v_pk_fma_f32 v[4:5], v[186:187], s[34:35], v[4:5] op_sel_hi:[1,0,1]
	v_add_u32_e32 v163, 0x100000, v162
	global_store_dwordx4 v163, v[16:19], s[14:15] offset:576
	v_add_u32_e32 v206, 0x120000, v162
	global_store_dwordx4 v206, v[12:15], s[14:15] offset:576
	v_add_u32_e32 v163, 0x140000, v162
	global_store_dwordx4 v163, v[8:11], s[14:15] offset:576
	v_add_u32_e32 v206, 0x160000, v162
	global_store_dwordx4 v206, v[4:7], s[14:15] offset:576
	s_and_b64 vcc, exec, s[6:7]
	s_mov_b64 s[8:9], -1
	s_cbranch_vccnz .LBB0_269
	s_andn2_b64 vcc, exec, s[10:11]
	s_cbranch_vccnz .LBB0_268
	s_barrier
	s_branch .LBB0_268
